# v210 + unit-loop heads of P2/P4/P9: 64-bit VALU has_next test replaced by a scalar 32-bit compare
# baseline (speedup 1.0000x reference)
.LBB0_122:
	s_add_i32 s86, s86, 1
	s_mul_i32 s2, s86, s33
	s_add_u32 s30, s2, s10
	s_mov_b32 s31, 0
	s_cmp_lt_u32 s30, 0x580
	s_cselect_b64 s[2:3], -1, 0
	s_cselect_b64 vcc, 0, -1
	s_cbranch_scc0 .LBB0_124
	s_ashr_i32 s8, s30, 31
	s_lshr_b32 s8, s8, 29
	s_add_i32 s8, s30, s8
	s_ashr_i32 s9, s8, 3
	s_and_b32 s8, s8, -8
	s_sub_i32 s8, s30, s8
	s_cmp_lt_i32 s8, 0
	s_cselect_b32 s11, s82, 0xb0
	s_mul_i32 s8, s8, s11
	s_add_i32 s8, s8, s9
	s_mul_hi_i32 s9, s8, 0x2e8ba2e9
	s_lshr_b32 s11, s9, 31
	s_ashr_i32 s9, s9, 4
	s_add_i32 s9, s9, s11
	s_lshl_b32 s11, s9, 2
	s_mulk_i32 s9, 0x58
	s_sub_i32 s8, s8, s9
	s_lshr_b32 s20, s8, 2
	s_and_b32 s8, s8, 3
	s_add_i32 s28, s11, s8

.LBB0_325:
	s_add_i32 s88, s88, 1
	s_mul_i32 s2, s88, s33
	s_add_u32 s64, s2, s10
	s_mov_b32 s65, 0
	s_cmp_lt_u32 s64, 0x300
	s_cselect_b64 s[2:3], -1, 0
	s_cselect_b64 vcc, 0, -1
	s_cbranch_scc0 .LBB0_327
	s_ashr_i32 s8, s64, 31
	s_lshr_b32 s8, s8, 29
	s_add_i32 s8, s64, s8
	s_ashr_i32 s9, s8, 3
	s_and_b32 s8, s8, -8
	s_sub_i32 s8, s64, s8
	s_cmp_lt_i32 s8, 0
	s_cselect_b32 s11, s83, 0x60
	s_mul_i32 s8, s8, s11
	s_add_i32 s8, s8, s9
	s_mul_hi_i32 s9, s8, 0x2aaaaaab
	s_lshr_b32 s11, s9, 31
	s_ashr_i32 s9, s9, 3
	s_add_i32 s9, s9, s11
	s_lshl_b32 s11, s9, 2
	s_mul_i32 s9, s9, 48
	s_sub_i32 s8, s8, s9
	s_lshr_b32 s20, s8, 2
	s_and_b32 s8, s8, 3
	s_add_i32 s26, s11, s8

.LBB0_616:
	s_add_i32 s68, s68, 1
	s_mul_i32 s2, s68, s33
	s_add_u32 s26, s2, s10
	s_mov_b32 s27, 0
	s_cmp_lt_u32 s26, 0x580
	s_cselect_b64 s[2:3], -1, 0
	s_cselect_b64 vcc, 0, -1
	s_cbranch_scc0 .LBB0_618
	s_ashr_i32 s8, s26, 31
	s_lshr_b32 s8, s8, 29
	s_add_i32 s8, s26, s8
	s_ashr_i32 s9, s8, 3
	s_and_b32 s8, s8, -8
	s_sub_i32 s8, s26, s8
	s_cmp_lt_i32 s8, 0
	s_cselect_b32 s11, s64, 0xb0
	s_mul_i32 s8, s8, s11
	s_add_i32 s8, s8, s9
	s_mul_hi_i32 s9, s8, 0x2e8ba2e9
	s_lshr_b32 s11, s9, 31
	s_ashr_i32 s9, s9, 4
	s_add_i32 s9, s9, s11
	s_lshl_b32 s11, s9, 2
	s_mulk_i32 s9, 0x58
	s_sub_i32 s8, s8, s9
	s_lshr_b32 s18, s8, 2
	s_and_b32 s8, s8, 3
	s_add_i32 s20, s11, s8
